# v15 + SwiGLU-tail peel + attention: mask blocks pipelined over 3 mask regs, max3-chain hazard nops removed
# speedup vs baseline: 1.0212x; 1.0063x over previous
.LBB0_267:
	v_or_b32_e32 v82, s8, v1
	v_and_b32_e32 v66, 63, v16
	v_lshlrev_b32_e32 v3, 6, v82
	s_movk_i32 s0, 0x3c0
	v_lshlrev_b32_e32 v16, 2, v82
	v_and_or_b32 v3, v3, s0, v18
	s_lshl_b32 s0, s3, 13
	v_and_b32_e32 v16, 32, v16
	v_bitop3_b32 v16, v3, s0, v16 bitop3:0xde
	v_lshl_or_b32 v3, v1, 6, v18
	s_lshl_b32 s0, s14, 12
	v_and_b32_e32 v2, 32, v2
	v_bitop3_b32 v67, v3, s0, v2 bitop3:0xde
	s_add_i32 m0, s35, 0x18000
	v_lshl_add_u64 v[2:3], v[10:11], 0, s[76:77]
	s_lshl_b32 s21, s14, 5
	s_waitcnt vmcnt(2)
	s_barrier
	global_load_lds_dwordx4 v[2:3], off
	v_lshl_add_u64 v[2:3], v[8:9], 0, s[76:77]
	s_add_i32 m0, s35, 0x1a000
	s_add_i32 s37, s35, 0x8000
	s_add_i32 s38, s35, 0xa000
	global_load_lds_dwordx4 v[2:3], off
	v_lshl_add_u64 v[2:3], v[6:7], 0, s[76:77]
	s_mov_b32 m0, s37
	s_add_u32 s8, s4, 0x40080
	global_load_lds_dwordx4 v[2:3], off
	v_lshl_add_u64 v[2:3], v[4:5], 0, s[76:77]
	s_mov_b32 m0, s38
	s_addc_u32 s9, s5, 0
	global_load_lds_dwordx4 v[2:3], off
	s_add_i32 m0, s35, 0x1c000
	v_lshl_add_u64 v[2:3], s[8:9], 0, v[50:51]
	global_load_lds_dwordx4 v[2:3], off
	v_lshl_add_u64 v[2:3], s[8:9], 0, v[46:47]
	s_add_i32 m0, s35, 0x1e000
	v_readlane_b32 s0, v254, 53
	global_load_lds_dwordx4 v[2:3], off
	v_lshlrev_b32_e32 v2, 14, v12
	v_and_b32_e32 v2, 0xffff8000, v2
	v_lshl_add_u32 v2, v13, 11, v2
	v_and_b32_e32 v3, 1, v12
	s_add_u32 s8, s26, s0
	v_lshl_or_b32 v2, v3, 6, v2
	s_addc_u32 s9, s1, 0
	v_lshl_add_u32 v2, v14, 1, v2
	v_mov_b32_e32 v3, v0
	v_lshl_add_u64 v[62:63], s[8:9], 0, v[2:3]
	v_lshlrev_b32_e32 v2, 14, v17
	v_and_b32_e32 v2, 0xffff8000, v2
	v_lshl_add_u32 v2, v15, 11, v2
	v_and_b32_e32 v3, 1, v17
	v_readlane_b32 s0, v254, 52
	v_lshl_or_b32 v2, v3, 6, v2
	s_add_u32 s40, s26, s0
	v_lshl_add_u32 v2, v19, 1, v2
	v_mov_b32_e32 v3, v0
	s_addc_u32 s41, s1, 0
	v_readlane_b32 s0, v254, 54
	v_lshl_add_u64 v[64:65], s[8:9], 0, v[2:3]
	s_add_u32 s0, s26, s0
	v_readlane_b32 s8, v254, 55
	s_addc_u32 s8, s1, s8
	s_add_u32 s1, s27, s30
	s_waitcnt vmcnt(6)
	s_addc_u32 s9, 0, 0
	s_add_u32 s1, s0, s1
	s_addc_u32 s26, s8, s9
	s_mov_b32 s27, -2
	s_mov_b64 s[8:9], 0
	v_add_u32_e32 v68, 0, v16
	s_barrier
	s_add_u32 s0, s40, s8
	s_addc_u32 s10, s41, s9
	s_add_u32 s0, s0, 0x7c00100
	s_addc_u32 s10, s10, 0
	s_add_u32 s30, s1, s8
	s_addc_u32 s11, s26, s9
	s_add_i32 s42, 0, 0x10000
	s_cmpk_eq_i32 s8, 0x700
	s_cselect_b32 s13, s7, s10
	s_cselect_b32 s12, s6, s0
	v_add_u32_e32 v69, s42, v67
	s_cselect_b32 s11, s5, s11
	s_cselect_b32 s10, s4, s30
	s_add_i32 s0, 0, 0x14000
	ds_read_b128 v[84:87], v69
	ds_read_b128 v[88:91], v69 offset:1024
	ds_read_b128 v[92:95], v69 offset:2048
	ds_read_b128 v[96:99], v69 offset:3072
	v_add_u32_e32 v69, s0, v67
	ds_read_b128 v[100:103], v69
	ds_read_b128 v[104:107], v69 offset:1024
	ds_read_b128 v[108:111], v69 offset:2048
	ds_read_b128 v[112:115], v69 offset:3072
	v_lshl_add_u64 v[148:149], v[64:65], 0, s[8:9]
	s_add_i32 m0, s35, 0xc000
	ds_read_b128 v[116:119], v68
	ds_read_b128 v[120:123], v68 offset:1024
	ds_read_b128 v[124:127], v68 offset:2048
	ds_read_b128 v[128:131], v68 offset:3072
	ds_read_b128 v[132:135], v68 offset:4096
	ds_read_b128 v[136:139], v68 offset:5120
	ds_read_b128 v[140:143], v68 offset:6144
	ds_read_b128 v[144:147], v68 offset:7168
	global_load_lds_dwordx4 v[148:149], off
	v_lshl_add_u64 v[148:149], v[62:63], 0, s[8:9]
	s_add_i32 m0, s35, 0xe000
	s_nop 0
	global_load_lds_dwordx4 v[148:149], off
	s_waitcnt vmcnt(8)
	s_waitcnt lgkmcnt(0)
	s_barrier
	s_setprio 1
	s_waitcnt lgkmcnt(0)
	v_mfma_f32_16x16x32_bf16 v[78:81], v[84:87], v[116:119], 0
	v_mfma_f32_16x16x32_bf16 v[70:73], v[92:95], v[116:119], 0
	v_mfma_f32_16x16x32_bf16 v[54:57], v[84:87], v[124:127], 0
	v_mfma_f32_16x16x32_bf16 v[38:41], v[92:95], v[124:127], 0
	v_mfma_f32_16x16x32_bf16 v[30:33], v[84:87], v[132:135], 0
	v_mfma_f32_16x16x32_bf16 v[22:25], v[92:95], v[132:135], 0
	v_mfma_f32_16x16x32_bf16 v[14:17], v[84:87], v[140:143], 0
	v_mfma_f32_16x16x32_bf16 v[6:9], v[92:95], v[140:143], 0
	v_mfma_f32_16x16x32_bf16 v[78:81], v[88:91], v[120:123], v[78:81]
	v_mfma_f32_16x16x32_bf16 v[70:73], v[96:99], v[120:123], v[70:73]
	v_mfma_f32_16x16x32_bf16 v[54:57], v[88:91], v[128:131], v[54:57]
	v_mfma_f32_16x16x32_bf16 v[38:41], v[96:99], v[128:131], v[38:41]
	v_mfma_f32_16x16x32_bf16 v[30:33], v[88:91], v[136:139], v[30:33]
	v_mfma_f32_16x16x32_bf16 v[22:25], v[96:99], v[136:139], v[22:25]
	v_mfma_f32_16x16x32_bf16 v[14:17], v[88:91], v[144:147], v[14:17]
	v_mfma_f32_16x16x32_bf16 v[6:9], v[96:99], v[144:147], v[6:9]
	s_setprio 0
	s_setprio 1
	v_mfma_f32_16x16x32_bf16 v[74:77], v[100:103], v[116:119], 0
	v_mfma_f32_16x16x32_bf16 v[58:61], v[108:111], v[116:119], 0
	v_mfma_f32_16x16x32_bf16 v[42:45], v[100:103], v[124:127], 0
	v_mfma_f32_16x16x32_bf16 v[34:37], v[108:111], v[124:127], 0
	v_mfma_f32_16x16x32_bf16 v[26:29], v[100:103], v[132:135], 0
	v_mfma_f32_16x16x32_bf16 v[18:21], v[108:111], v[132:135], 0
	v_mfma_f32_16x16x32_bf16 v[10:13], v[100:103], v[140:143], 0
	v_mfma_f32_16x16x32_bf16 v[2:5], v[108:111], v[140:143], 0
	v_mfma_f32_16x16x32_bf16 v[74:77], v[104:107], v[120:123], v[74:77]
	v_mfma_f32_16x16x32_bf16 v[58:61], v[112:115], v[120:123], v[58:61]
	v_mfma_f32_16x16x32_bf16 v[42:45], v[104:107], v[128:131], v[42:45]
	v_mfma_f32_16x16x32_bf16 v[34:37], v[112:115], v[128:131], v[34:37]
	v_mfma_f32_16x16x32_bf16 v[26:29], v[104:107], v[136:139], v[26:29]
	v_mfma_f32_16x16x32_bf16 v[18:21], v[112:115], v[136:139], v[18:21]
	v_mfma_f32_16x16x32_bf16 v[10:13], v[104:107], v[144:147], v[10:13]
	v_mfma_f32_16x16x32_bf16 v[2:5], v[112:115], v[144:147], v[2:5]
	s_setprio 0
	s_barrier
	s_add_i32 s30, s42, s20
	v_lshl_add_u64 v[148:149], s[10:11], 0, v[50:51]
	s_mov_b32 m0, s30
	v_lshl_add_u64 v[150:151], s[10:11], 0, v[46:47]
	global_load_lds_dwordx4 v[148:149], off
	s_add_i32 m0, s30, 0x2000
	s_add_u32 s42, s10, 0x40000
	s_addc_u32 s43, s11, 0
	s_add_i32 s0, s0, s20
	global_load_lds_dwordx4 v[150:151], off
	v_lshl_add_u64 v[84:85], s[42:43], 0, v[50:51]
	s_mov_b32 m0, s0
	v_lshl_add_u64 v[152:153], s[12:13], 0, v[52:53]
	global_load_lds_dwordx4 v[84:85], off
	v_lshl_add_u64 v[84:85], s[42:43], 0, v[46:47]
	s_add_i32 m0, s0, 0x2000
	v_lshl_add_u64 v[154:155], s[12:13], 0, v[48:49]
	global_load_lds_dwordx4 v[84:85], off
	s_mov_b32 m0, s35
	s_nop 0
	global_load_lds_dwordx4 v[152:153], off
	s_mov_b32 m0, s31
	s_nop 0
	global_load_lds_dwordx4 v[154:155], off
	s_waitcnt vmcnt(8)
	s_waitcnt lgkmcnt(0)
	s_barrier
	s_barrier
	s_add_i32 s0, 0, 0x18000
	v_add_u32_e32 v69, s0, v67
	s_add_i32 s12, 0, 0x1c000
	ds_read_b128 v[84:87], v69
	ds_read_b128 v[88:91], v69 offset:1024
	ds_read_b128 v[92:95], v69 offset:2048
	ds_read_b128 v[96:99], v69 offset:3072
	v_add_u32_e32 v69, s12, v67
	ds_read_b128 v[100:103], v69
	ds_read_b128 v[104:107], v69 offset:1024
	ds_read_b128 v[108:111], v69 offset:2048
	ds_read_b128 v[112:115], v69 offset:3072
	s_mov_b32 m0, s34
	ds_read_b128 v[116:119], v68 offset:32768
	ds_read_b128 v[120:123], v68 offset:33792
	ds_read_b128 v[124:127], v68 offset:34816
	ds_read_b128 v[128:131], v68 offset:35840
	ds_read_b128 v[132:135], v68 offset:36864
	ds_read_b128 v[136:139], v68 offset:37888
	ds_read_b128 v[140:143], v68 offset:38912
	ds_read_b128 v[144:147], v68 offset:39936
	global_load_lds_dwordx4 v[152:153], off
	s_mov_b32 m0, s36
	s_nop 0
	global_load_lds_dwordx4 v[154:155], off
	s_waitcnt vmcnt(8)
	s_waitcnt lgkmcnt(0)
	s_barrier
	s_setprio 1
	s_waitcnt lgkmcnt(0)
	v_mfma_f32_16x16x32_bf16 v[78:81], v[84:87], v[116:119], v[78:81]
	v_mfma_f32_16x16x32_bf16 v[70:73], v[92:95], v[116:119], v[70:73]
	v_mfma_f32_16x16x32_bf16 v[54:57], v[84:87], v[124:127], v[54:57]
	v_mfma_f32_16x16x32_bf16 v[38:41], v[92:95], v[124:127], v[38:41]
	v_mfma_f32_16x16x32_bf16 v[30:33], v[84:87], v[132:135], v[30:33]
	v_mfma_f32_16x16x32_bf16 v[22:25], v[92:95], v[132:135], v[22:25]
	v_mfma_f32_16x16x32_bf16 v[14:17], v[84:87], v[140:143], v[14:17]
	v_mfma_f32_16x16x32_bf16 v[6:9], v[92:95], v[140:143], v[6:9]
	v_mfma_f32_16x16x32_bf16 v[78:81], v[88:91], v[120:123], v[78:81]
	v_mfma_f32_16x16x32_bf16 v[70:73], v[96:99], v[120:123], v[70:73]
	v_mfma_f32_16x16x32_bf16 v[54:57], v[88:91], v[128:131], v[54:57]
	v_mfma_f32_16x16x32_bf16 v[38:41], v[96:99], v[128:131], v[38:41]
	v_mfma_f32_16x16x32_bf16 v[30:33], v[88:91], v[136:139], v[30:33]
	v_mfma_f32_16x16x32_bf16 v[22:25], v[96:99], v[136:139], v[22:25]
	v_mfma_f32_16x16x32_bf16 v[14:17], v[88:91], v[144:147], v[14:17]
	v_mfma_f32_16x16x32_bf16 v[6:9], v[96:99], v[144:147], v[6:9]
	s_setprio 0
	s_setprio 1
	v_mfma_f32_16x16x32_bf16 v[74:77], v[100:103], v[116:119], v[74:77]
	v_mfma_f32_16x16x32_bf16 v[58:61], v[108:111], v[116:119], v[58:61]
	v_mfma_f32_16x16x32_bf16 v[42:45], v[100:103], v[124:127], v[42:45]
	v_mfma_f32_16x16x32_bf16 v[34:37], v[108:111], v[124:127], v[34:37]
	v_mfma_f32_16x16x32_bf16 v[26:29], v[100:103], v[132:135], v[26:29]
	v_mfma_f32_16x16x32_bf16 v[18:21], v[108:111], v[132:135], v[18:21]
	v_mfma_f32_16x16x32_bf16 v[10:13], v[100:103], v[140:143], v[10:13]
	v_mfma_f32_16x16x32_bf16 v[2:5], v[108:111], v[140:143], v[2:5]
	v_mfma_f32_16x16x32_bf16 v[74:77], v[104:107], v[120:123], v[74:77]
	v_mfma_f32_16x16x32_bf16 v[58:61], v[112:115], v[120:123], v[58:61]
	v_mfma_f32_16x16x32_bf16 v[42:45], v[104:107], v[128:131], v[42:45]
	v_mfma_f32_16x16x32_bf16 v[34:37], v[112:115], v[128:131], v[34:37]
	v_mfma_f32_16x16x32_bf16 v[26:29], v[104:107], v[136:139], v[26:29]
	v_mfma_f32_16x16x32_bf16 v[18:21], v[112:115], v[136:139], v[18:21]
	v_mfma_f32_16x16x32_bf16 v[10:13], v[104:107], v[144:147], v[10:13]
	v_mfma_f32_16x16x32_bf16 v[2:5], v[112:115], v[144:147], v[2:5]
	s_setprio 0
	s_barrier
	s_add_i32 s0, s0, s20
	v_lshl_add_u64 v[84:85], v[148:149], 0, s[76:77]
	s_mov_b32 m0, s0
	s_nop 0
	global_load_lds_dwordx4 v[84:85], off
	s_add_i32 m0, s0, 0x2000
	s_add_u32 s10, s10, 0x40080
	v_lshl_add_u64 v[84:85], v[150:151], 0, s[76:77]
	s_addc_u32 s11, s11, 0
	s_add_i32 s0, s12, s20
	global_load_lds_dwordx4 v[84:85], off
	v_lshl_add_u64 v[84:85], s[10:11], 0, v[50:51]
	s_mov_b32 m0, s0
	s_nop 0
	global_load_lds_dwordx4 v[84:85], off
	v_lshl_add_u64 v[84:85], s[10:11], 0, v[46:47]
	s_add_i32 m0, s0, 0x2000
	s_nop 0
	global_load_lds_dwordx4 v[84:85], off
	v_lshl_add_u64 v[84:85], v[152:153], 0, s[76:77]
	s_mov_b32 m0, s37
	s_nop 0
	global_load_lds_dwordx4 v[84:85], off
	v_lshl_add_u64 v[84:85], v[154:155], 0, s[76:77]
	s_mov_b32 m0, s38
	s_nop 0
	global_load_lds_dwordx4 v[84:85], off
	s_waitcnt vmcnt(8)
	s_waitcnt lgkmcnt(0)
	s_barrier
	s_barrier
	s_add_i32 s27, s27, 2
	s_add_u32 s8, s8, 0x100
	s_addc_u32 s9, s9, 0

.LBB0_493:
	s_cmp_lt_i32 s14, s34
	s_cselect_b64 s[4:5], -1, 0
	s_and_b64 s[4:5], s[10:11], s[4:5]
	s_add_i32 s15, s12, 64
	s_cmp_lt_u32 s12, 0xfffffeff
	s_cselect_b64 s[12:13], -1, 0
	s_and_b64 s[12:13], s[4:5], s[12:13]
	s_and_b64 vcc, exec, s[12:13]
	s_cbranch_vccnz .LBB0_503
	s_cmp_lt_u32 s15, 0xffffff7f
	s_cselect_b64 s[12:13], -1, 0
	s_and_b64 s[12:13], s[4:5], s[12:13]
	ds_read_b128 v[10:13], v217
	ds_read_b128 v[244:247], v217 offset:32
	v_xor_b32_e32 v112, 0x80000000, v197
	v_xor_b32_e32 v80, 0x80000000, v239
	v_mov_b32_e32 v113, v112
	v_mov_b32_e32 v114, v112
	v_mov_b32_e32 v115, v112
	v_mov_b32_e32 v116, v112
	v_mov_b32_e32 v117, v112
	v_mov_b32_e32 v118, v112
	v_mov_b32_e32 v119, v112
	v_mov_b32_e32 v120, v112
	v_mov_b32_e32 v121, v112
	v_mov_b32_e32 v122, v112
	v_mov_b32_e32 v123, v112
	v_mov_b32_e32 v124, v112
	v_mov_b32_e32 v125, v112
	v_mov_b32_e32 v126, v112
	v_mov_b32_e32 v127, v112
	v_mov_b32_e32 v81, v80
	v_mov_b32_e32 v82, v80
	v_mov_b32_e32 v83, v80
	v_mov_b32_e32 v84, v80
	v_mov_b32_e32 v85, v80
	v_mov_b32_e32 v86, v80
	v_mov_b32_e32 v87, v80
	v_mov_b32_e32 v88, v80
	v_mov_b32_e32 v89, v80
	v_mov_b32_e32 v90, v80
	v_mov_b32_e32 v91, v80
	v_mov_b32_e32 v92, v80
	v_mov_b32_e32 v93, v80
	v_mov_b32_e32 v94, v80
	v_mov_b32_e32 v95, v80
	s_waitcnt lgkmcnt(1)
	v_mfma_f32_32x32x16_bf16 v[128:143], v[10:13], v[144:147], v[112:127]
	ds_read_b128 v[204:207], v218
	ds_read_b128 v[248:251], v217 offset:64
	ds_read_b128 v[230:233], v217 offset:96
	v_mfma_f32_32x32x16_bf16 v[96:111], v[10:13], v[160:163], v[80:95]
	ds_read_b128 v[10:13], v218 offset:32
	s_waitcnt lgkmcnt(4)
	v_mfma_f32_32x32x16_bf16 v[128:143], v[244:247], v[148:151], v[128:143]
	v_mfma_f32_32x32x16_bf16 v[96:111], v[244:247], v[164:167], v[96:111]
	s_waitcnt lgkmcnt(3)
	v_mfma_f32_32x32x16_bf16 v[112:127], v[204:207], v[144:147], v[112:127]
	v_mfma_f32_32x32x16_bf16 v[80:95], v[204:207], v[160:163], v[80:95]
	ds_read_b128 v[204:207], v218 offset:64
	s_waitcnt lgkmcnt(3)
	v_mfma_f32_32x32x16_bf16 v[128:143], v[248:251], v[152:155], v[128:143]
	v_mfma_f32_32x32x16_bf16 v[96:111], v[248:251], v[168:171], v[96:111]
	s_waitcnt lgkmcnt(1)
	v_mfma_f32_32x32x16_bf16 v[80:95], v[10:13], v[164:167], v[80:95]
	v_mfma_f32_32x32x16_bf16 v[112:127], v[10:13], v[148:151], v[112:127]
	v_mfma_f32_32x32x16_bf16 v[128:143], v[230:233], v[156:159], v[128:143]
	v_mfma_f32_32x32x16_bf16 v[96:111], v[230:233], v[172:175], v[96:111]
	ds_read_b128 v[230:233], v218 offset:96
	s_waitcnt lgkmcnt(1)
	v_mfma_f32_32x32x16_bf16 v[80:95], v[204:207], v[168:171], v[80:95]
	v_mfma_f32_32x32x16_bf16 v[112:127], v[204:207], v[152:155], v[112:127]
	s_waitcnt lgkmcnt(0)
	v_mfma_f32_32x32x16_bf16 v[80:95], v[230:233], v[172:175], v[80:95]
	v_mfma_f32_32x32x16_bf16 v[112:127], v[230:233], v[156:159], v[112:127]
	v_cndmask_b32_e64 v1, 0, 1, s[12:13]
	v_cmp_ne_u32_e64 s[4:5], 1, v1
	s_andn2_b64 vcc, exec, s[12:13]
	s_cbranch_vccnz .LBB0_496
	v_add_u32_e32 v1, v193, v240
	v_add_u32_e32 v12, 0xffffff7f, v1
	v_cmp_lt_u32_e32 vcc, s91, v12
	v_add_u32_e32 v13, 0xffffff5f, v1
	v_cmp_lt_u32_e64 s[20:21], s91, v13
	v_add_u32_e32 v14, 0xffffff7e, v1
	v_cmp_lt_u32_e64 s[40:41], s91, v14
	v_cndmask_b32_e32 v128, v234, v128, vcc
	v_add_u32_e32 v12, 0xffffff5e, v1
	v_cmp_lt_u32_e32 vcc, s91, v12
	v_cndmask_b32_e64 v112, v234, v112, s[20:21]
	v_add_u32_e32 v13, 0xffffff7d, v1
	v_cmp_lt_u32_e64 s[20:21], s91, v13
	v_cndmask_b32_e64 v129, v234, v129, s[40:41]
	v_add_u32_e32 v14, 0xffffff5d, v1
	v_cmp_lt_u32_e64 s[40:41], s91, v14
	v_cndmask_b32_e32 v113, v234, v113, vcc
	v_add_u32_e32 v12, 0xffffff7c, v1
	v_cmp_lt_u32_e32 vcc, s91, v12
	v_cndmask_b32_e64 v130, v234, v130, s[20:21]
	v_add_u32_e32 v13, 0xffffff5c, v1
	v_cmp_lt_u32_e64 s[20:21], s91, v13
	v_cndmask_b32_e64 v114, v234, v114, s[40:41]
	v_add_u32_e32 v14, 0xffffff77, v1
	v_cmp_lt_u32_e64 s[40:41], s91, v14
	v_cndmask_b32_e32 v131, v234, v131, vcc
	v_add_u32_e32 v12, 0xffffff57, v1
	v_cmp_lt_u32_e32 vcc, s91, v12
	v_cndmask_b32_e64 v115, v234, v115, s[20:21]
	v_add_u32_e32 v13, 0xffffff76, v1
	v_cmp_lt_u32_e64 s[20:21], s91, v13
	v_cndmask_b32_e64 v132, v234, v132, s[40:41]
	v_add_u32_e32 v14, 0xffffff56, v1
	v_cmp_lt_u32_e64 s[40:41], s91, v14
	v_cndmask_b32_e32 v116, v234, v116, vcc
	v_add_u32_e32 v12, 0xffffff75, v1
	v_cmp_lt_u32_e32 vcc, s91, v12
	v_cndmask_b32_e64 v133, v234, v133, s[20:21]
	v_add_u32_e32 v13, 0xffffff55, v1
	v_cmp_lt_u32_e64 s[20:21], s91, v13
	v_cndmask_b32_e64 v117, v234, v117, s[40:41]
	v_add_u32_e32 v14, 0xffffff74, v1
	v_cmp_lt_u32_e64 s[40:41], s91, v14
	v_cndmask_b32_e32 v134, v234, v134, vcc
	v_add_u32_e32 v12, 0xffffff54, v1
	v_cmp_lt_u32_e32 vcc, s91, v12
	v_cndmask_b32_e64 v118, v234, v118, s[20:21]
	v_add_u32_e32 v13, 0xffffff6f, v1
	v_cmp_lt_u32_e64 s[20:21], s91, v13
	v_cndmask_b32_e64 v135, v234, v135, s[40:41]
	v_add_u32_e32 v14, 0xffffff4f, v1
	v_cmp_lt_u32_e64 s[40:41], s91, v14
	v_cndmask_b32_e32 v119, v234, v119, vcc
	v_add_u32_e32 v12, 0xffffff6e, v1
	v_cmp_lt_u32_e32 vcc, s91, v12
	v_cndmask_b32_e64 v136, v234, v136, s[20:21]
	v_add_u32_e32 v13, 0xffffff4e, v1
	v_cmp_lt_u32_e64 s[20:21], s91, v13
	v_cndmask_b32_e64 v120, v234, v120, s[40:41]
	v_add_u32_e32 v14, 0xffffff6d, v1
	v_cmp_lt_u32_e64 s[40:41], s91, v14
	v_cndmask_b32_e32 v137, v234, v137, vcc
	v_add_u32_e32 v12, 0xffffff4d, v1
	v_cmp_lt_u32_e32 vcc, s91, v12
	v_cndmask_b32_e64 v121, v234, v121, s[20:21]
	v_add_u32_e32 v13, 0xffffff6c, v1
	v_cmp_lt_u32_e64 s[20:21], s91, v13
	v_cndmask_b32_e64 v138, v234, v138, s[40:41]
	v_add_u32_e32 v14, 0xffffff4c, v1
	v_cmp_lt_u32_e64 s[40:41], s91, v14
	v_cndmask_b32_e32 v122, v234, v122, vcc
	v_add_u32_e32 v12, 0xffffff67, v1
	v_cmp_lt_u32_e32 vcc, s91, v12
	v_cndmask_b32_e64 v139, v234, v139, s[20:21]
	v_add_u32_e32 v13, 0xffffff47, v1
	v_cmp_lt_u32_e64 s[20:21], s91, v13
	v_cndmask_b32_e64 v123, v234, v123, s[40:41]
	v_add_u32_e32 v14, 0xffffff66, v1
	v_cmp_lt_u32_e64 s[40:41], s91, v14
	v_cndmask_b32_e32 v140, v234, v140, vcc
	v_add_u32_e32 v12, 0xffffff46, v1
	v_cmp_lt_u32_e32 vcc, s91, v12
	v_cndmask_b32_e64 v124, v234, v124, s[20:21]
	v_add_u32_e32 v13, 0xffffff65, v1
	v_cmp_lt_u32_e64 s[20:21], s91, v13
	v_cndmask_b32_e64 v141, v234, v141, s[40:41]
	v_add_u32_e32 v14, 0xffffff45, v1
	v_cmp_lt_u32_e64 s[40:41], s91, v14
	v_cndmask_b32_e32 v125, v234, v125, vcc
	v_add_u32_e32 v12, 0xffffff64, v1
	v_cmp_lt_u32_e32 vcc, s91, v12
	v_cndmask_b32_e64 v142, v234, v142, s[20:21]
	v_add_u32_e32 v13, 0xffffff44, v1
	v_cmp_lt_u32_e64 s[20:21], s91, v13
	v_cndmask_b32_e64 v126, v234, v126, s[40:41]
	s_nop 0
	v_cndmask_b32_e32 v143, v234, v143, vcc
	v_cndmask_b32_e64 v127, v234, v127, s[20:21]
.LBB0_496:
	v_max3_f32 v1, v0, v128, v112
	v_cmp_lt_i32_e32 vcc, v228, v222
	v_max3_f32 v1, v1, v129, v113
	v_max3_f32 v1, v1, v130, v114
	v_max3_f32 v1, v1, v131, v115
	v_cndmask_b32_e32 v10, v221, v228, vcc
	v_max3_f32 v1, v1, v132, v116
	v_lshlrev_b32_e32 v243, 2, v10
	v_max3_f32 v1, v1, v133, v117
	v_max3_f32 v1, v1, v134, v118
	v_max3_f32 v1, v1, v135, v119
	v_max3_f32 v1, v1, v136, v120
	v_max3_f32 v1, v1, v137, v121
	v_max3_f32 v1, v1, v138, v122
	v_max3_f32 v1, v1, v139, v123
	v_max3_f32 v1, v1, v140, v124
	v_max3_f32 v1, v1, v141, v125
	v_max3_f32 v1, v1, v142, v126
	v_max3_f32 v1, v1, v143, v127
	ds_bpermute_b32 v10, v243, v1
	s_waitcnt lgkmcnt(0)
	v_max3_f32 v1, v1, v1, v10
	v_cmp_lt_f32_e32 vcc, s33, v1
	s_cbranch_vccz .LBB0_498
	v_exp_f32_e64 v10, -v1
	v_add_f32_e32 v197, v197, v1
	v_sub_f32_e32 v143, v143, v1
	v_sub_f32_e32 v142, v142, v1
	v_sub_f32_e32 v141, v141, v1
	v_sub_f32_e32 v140, v140, v1
	v_sub_f32_e32 v139, v139, v1
	v_sub_f32_e32 v138, v138, v1
	v_sub_f32_e32 v137, v137, v1
	v_sub_f32_e32 v136, v136, v1
	v_sub_f32_e32 v135, v135, v1
	v_sub_f32_e32 v134, v134, v1
	v_sub_f32_e32 v133, v133, v1
	v_sub_f32_e32 v132, v132, v1
	v_sub_f32_e32 v131, v131, v1
	v_sub_f32_e32 v130, v130, v1
	v_sub_f32_e32 v129, v129, v1
	v_sub_f32_e32 v128, v128, v1
	v_pk_mul_f32 v[78:79], v[78:79], v[10:11] op_sel_hi:[1,0]
	v_pk_mul_f32 v[76:77], v[76:77], v[10:11] op_sel_hi:[1,0]
	v_pk_mul_f32 v[74:75], v[74:75], v[10:11] op_sel_hi:[1,0]
	v_pk_mul_f32 v[72:73], v[72:73], v[10:11] op_sel_hi:[1,0]
	v_pk_mul_f32 v[70:71], v[70:71], v[10:11] op_sel_hi:[1,0]
	v_pk_mul_f32 v[68:69], v[68:69], v[10:11] op_sel_hi:[1,0]
	v_pk_mul_f32 v[66:67], v[66:67], v[10:11] op_sel_hi:[1,0]
	v_pk_mul_f32 v[64:65], v[64:65], v[10:11] op_sel_hi:[1,0]
	v_pk_mul_f32 v[62:63], v[62:63], v[10:11] op_sel_hi:[1,0]
	v_pk_mul_f32 v[60:61], v[60:61], v[10:11] op_sel_hi:[1,0]
	v_pk_mul_f32 v[58:59], v[58:59], v[10:11] op_sel_hi:[1,0]
	v_pk_mul_f32 v[56:57], v[56:57], v[10:11] op_sel_hi:[1,0]
	v_pk_mul_f32 v[54:55], v[54:55], v[10:11] op_sel_hi:[1,0]
	v_pk_mul_f32 v[52:53], v[52:53], v[10:11] op_sel_hi:[1,0]
	v_pk_mul_f32 v[50:51], v[50:51], v[10:11] op_sel_hi:[1,0]
	v_pk_mul_f32 v[48:49], v[48:49], v[10:11] op_sel_hi:[1,0]
	v_mul_f32_e32 v241, v241, v10
	v_sub_f32_e32 v127, v127, v1
	v_sub_f32_e32 v126, v126, v1
	v_sub_f32_e32 v125, v125, v1
	v_sub_f32_e32 v124, v124, v1
	v_sub_f32_e32 v123, v123, v1
	v_sub_f32_e32 v122, v122, v1
	v_sub_f32_e32 v121, v121, v1
	v_sub_f32_e32 v120, v120, v1
	v_sub_f32_e32 v119, v119, v1
	v_sub_f32_e32 v118, v118, v1
	v_sub_f32_e32 v117, v117, v1
	v_sub_f32_e32 v116, v116, v1
	v_sub_f32_e32 v115, v115, v1
	v_sub_f32_e32 v114, v114, v1
	v_sub_f32_e32 v113, v113, v1
	v_sub_f32_e32 v112, v112, v1
.LBB0_498:
	v_exp_f32_e32 v14, v128
	v_exp_f32_e32 v112, v112
	v_exp_f32_e32 v15, v129
	v_exp_f32_e32 v113, v113
	v_exp_f32_e32 v204, v130
	v_exp_f32_e32 v206, v114
	v_exp_f32_e32 v205, v131
	v_exp_f32_e32 v207, v115
	v_exp_f32_e32 v10, v132
	v_exp_f32_e32 v12, v116
	v_exp_f32_e32 v11, v133
	v_exp_f32_e32 v13, v117
	v_exp_f32_e32 v128, v134
	v_exp_f32_e32 v130, v118
	v_exp_f32_e32 v129, v135
	v_exp_f32_e32 v131, v119
	v_exp_f32_e32 v118, v136
	v_exp_f32_e32 v120, v120
	v_exp_f32_e32 v119, v137
	v_exp_f32_e32 v121, v121
	v_exp_f32_e32 v132, v138
	v_exp_f32_e32 v134, v122
	v_exp_f32_e32 v133, v139
	v_exp_f32_e32 v135, v123
	v_exp_f32_e32 v114, v140
	v_exp_f32_e32 v116, v124
	v_exp_f32_e32 v115, v141
	v_exp_f32_e32 v117, v125
	v_exp_f32_e32 v122, v142
	v_exp_f32_e32 v124, v126
	v_exp_f32_e32 v123, v143
	v_exp_f32_e32 v125, v127
	ds_read_b64_tr_b16 v[136:137], v219 offset:9216
	ds_read_b64_tr_b16 v[138:139], v219 offset:10752
	v_cvt_pk_bf16_f32 v140, v14, v15
	v_cvt_pk_bf16_f32 v141, v204, v205
	v_cvt_pk_bf16_f32 v142, v10, v11
	v_cvt_pk_bf16_f32 v143, v128, v129
	v_cvt_pk_bf16_f32 v230, v118, v119
	v_cvt_pk_bf16_f32 v231, v132, v133
	v_cvt_pk_bf16_f32 v232, v114, v115
	v_cvt_pk_bf16_f32 v233, v122, v123
	s_waitcnt lgkmcnt(0)
	v_mfma_f32_32x32x16_bf16 v[64:79], v[136:139], v[140:143], v[64:79]
	ds_read_b64_tr_b16 v[136:137], v219 offset:12288
	ds_read_b64_tr_b16 v[138:139], v219 offset:13824
	v_cvt_pk_bf16_f32 v244, v112, v113
	v_cvt_pk_bf16_f32 v245, v206, v207
	v_cvt_pk_bf16_f32 v246, v12, v13
	v_cvt_pk_bf16_f32 v247, v130, v131
	v_cvt_pk_bf16_f32 v248, v120, v121
	v_cvt_pk_bf16_f32 v249, v134, v135
	v_cvt_pk_bf16_f32 v250, v116, v117
	s_waitcnt lgkmcnt(0)
	v_mfma_f32_32x32x16_bf16 v[64:79], v[136:139], v[230:233], v[64:79]
	ds_read_b64_tr_b16 v[136:137], v219 offset:15360
	ds_read_b64_tr_b16 v[138:139], v219 offset:16896
	v_cvt_pk_bf16_f32 v251, v124, v125
	s_waitcnt lgkmcnt(0)
	v_mfma_f32_32x32x16_bf16 v[64:79], v[136:139], v[244:247], v[64:79]
	ds_read_b64_tr_b16 v[136:137], v219 offset:18432
	ds_read_b64_tr_b16 v[138:139], v219 offset:19968
	s_waitcnt lgkmcnt(0)
	v_mfma_f32_32x32x16_bf16 v[64:79], v[136:139], v[248:251], v[64:79]
	ds_read_b64_tr_b16 v[136:137], v219 offset:9280
	ds_read_b64_tr_b16 v[138:139], v219 offset:10816
	s_waitcnt lgkmcnt(0)
	v_mfma_f32_32x32x16_bf16 v[48:63], v[136:139], v[140:143], v[48:63]
	ds_read_b64_tr_b16 v[136:137], v219 offset:12352
	ds_read_b64_tr_b16 v[138:139], v219 offset:13888
	s_waitcnt lgkmcnt(0)
	v_mfma_f32_32x32x16_bf16 v[48:63], v[136:139], v[230:233], v[48:63]
	ds_read_b64_tr_b16 v[136:137], v219 offset:15424
	ds_read_b64_tr_b16 v[138:139], v219 offset:16960
	s_waitcnt lgkmcnt(0)
	v_mfma_f32_32x32x16_bf16 v[48:63], v[136:139], v[244:247], v[48:63]
	ds_read_b64_tr_b16 v[136:137], v219 offset:18496
	ds_read_b64_tr_b16 v[138:139], v219 offset:20032
	s_waitcnt lgkmcnt(0)
	v_mfma_f32_32x32x16_bf16 v[48:63], v[136:139], v[248:251], v[48:63]
	s_and_b64 vcc, exec, s[4:5]
	s_cbranch_vccnz .LBB0_500
	v_add_u32_e32 v127, v212, v240
	v_add_u32_e32 v138, 0xffffff7f, v127
	v_cmp_lt_u32_e32 vcc, s91, v138
	v_add_u32_e32 v139, 0xffffff5f, v127
	v_cmp_lt_u32_e64 s[20:21], s91, v139
	v_add_u32_e32 v140, 0xffffff7e, v127
	v_cmp_lt_u32_e64 s[40:41], s91, v140
	v_cndmask_b32_e32 v96, v234, v96, vcc
	v_add_u32_e32 v138, 0xffffff5e, v127
	v_cmp_lt_u32_e32 vcc, s91, v138
	v_cndmask_b32_e64 v80, v234, v80, s[20:21]
	v_add_u32_e32 v139, 0xffffff7d, v127
	v_cmp_lt_u32_e64 s[20:21], s91, v139
	v_cndmask_b32_e64 v97, v234, v97, s[40:41]
	v_add_u32_e32 v140, 0xffffff5d, v127
	v_cmp_lt_u32_e64 s[40:41], s91, v140
	v_cndmask_b32_e32 v81, v234, v81, vcc
	v_add_u32_e32 v138, 0xffffff7c, v127
	v_cmp_lt_u32_e32 vcc, s91, v138
	v_cndmask_b32_e64 v98, v234, v98, s[20:21]
	v_add_u32_e32 v139, 0xffffff5c, v127
	v_cmp_lt_u32_e64 s[20:21], s91, v139
	v_cndmask_b32_e64 v82, v234, v82, s[40:41]
	v_add_u32_e32 v140, 0xffffff77, v127
	v_cmp_lt_u32_e64 s[40:41], s91, v140
	v_cndmask_b32_e32 v99, v234, v99, vcc
	v_add_u32_e32 v138, 0xffffff57, v127
	v_cmp_lt_u32_e32 vcc, s91, v138
	v_cndmask_b32_e64 v83, v234, v83, s[20:21]
	v_add_u32_e32 v139, 0xffffff76, v127
	v_cmp_lt_u32_e64 s[20:21], s91, v139
	v_cndmask_b32_e64 v100, v234, v100, s[40:41]
	v_add_u32_e32 v140, 0xffffff56, v127
	v_cmp_lt_u32_e64 s[40:41], s91, v140
	v_cndmask_b32_e32 v84, v234, v84, vcc
	v_add_u32_e32 v138, 0xffffff75, v127
	v_cmp_lt_u32_e32 vcc, s91, v138
	v_cndmask_b32_e64 v101, v234, v101, s[20:21]
	v_add_u32_e32 v139, 0xffffff55, v127
	v_cmp_lt_u32_e64 s[20:21], s91, v139
	v_cndmask_b32_e64 v85, v234, v85, s[40:41]
	v_add_u32_e32 v140, 0xffffff74, v127
	v_cmp_lt_u32_e64 s[40:41], s91, v140
	v_cndmask_b32_e32 v102, v234, v102, vcc
	v_add_u32_e32 v138, 0xffffff54, v127
	v_cmp_lt_u32_e32 vcc, s91, v138
	v_cndmask_b32_e64 v86, v234, v86, s[20:21]
	v_add_u32_e32 v139, 0xffffff6f, v127
	v_cmp_lt_u32_e64 s[20:21], s91, v139
	v_cndmask_b32_e64 v103, v234, v103, s[40:41]
	v_add_u32_e32 v140, 0xffffff4f, v127
	v_cmp_lt_u32_e64 s[40:41], s91, v140
	v_cndmask_b32_e32 v87, v234, v87, vcc
	v_add_u32_e32 v138, 0xffffff6e, v127
	v_cmp_lt_u32_e32 vcc, s91, v138
	v_cndmask_b32_e64 v104, v234, v104, s[20:21]
	v_add_u32_e32 v139, 0xffffff4e, v127
	v_cmp_lt_u32_e64 s[20:21], s91, v139
	v_cndmask_b32_e64 v88, v234, v88, s[40:41]
	v_add_u32_e32 v140, 0xffffff6d, v127
	v_cmp_lt_u32_e64 s[40:41], s91, v140
	v_cndmask_b32_e32 v105, v234, v105, vcc
	v_add_u32_e32 v138, 0xffffff4d, v127
	v_cmp_lt_u32_e32 vcc, s91, v138
	v_cndmask_b32_e64 v89, v234, v89, s[20:21]
	v_add_u32_e32 v139, 0xffffff6c, v127
	v_cmp_lt_u32_e64 s[20:21], s91, v139
	v_cndmask_b32_e64 v106, v234, v106, s[40:41]
	v_add_u32_e32 v140, 0xffffff4c, v127
	v_cmp_lt_u32_e64 s[40:41], s91, v140
	v_cndmask_b32_e32 v90, v234, v90, vcc
	v_add_u32_e32 v138, 0xffffff67, v127
	v_cmp_lt_u32_e32 vcc, s91, v138
	v_cndmask_b32_e64 v107, v234, v107, s[20:21]
	v_add_u32_e32 v139, 0xffffff47, v127
	v_cmp_lt_u32_e64 s[20:21], s91, v139
	v_cndmask_b32_e64 v91, v234, v91, s[40:41]
	v_add_u32_e32 v140, 0xffffff66, v127
	v_cmp_lt_u32_e64 s[40:41], s91, v140
	v_cndmask_b32_e32 v108, v234, v108, vcc
	v_add_u32_e32 v138, 0xffffff46, v127
	v_cmp_lt_u32_e32 vcc, s91, v138
	v_cndmask_b32_e64 v92, v234, v92, s[20:21]
	v_add_u32_e32 v139, 0xffffff65, v127
	v_cmp_lt_u32_e64 s[20:21], s91, v139
	v_cndmask_b32_e64 v109, v234, v109, s[40:41]
	v_add_u32_e32 v140, 0xffffff45, v127
	v_cmp_lt_u32_e64 s[40:41], s91, v140
	v_cndmask_b32_e32 v93, v234, v93, vcc
	v_add_u32_e32 v138, 0xffffff64, v127
	v_cmp_lt_u32_e32 vcc, s91, v138
	v_cndmask_b32_e64 v110, v234, v110, s[20:21]
	v_add_u32_e32 v139, 0xffffff44, v127
	v_cmp_lt_u32_e64 s[20:21], s91, v139
	v_cndmask_b32_e64 v94, v234, v94, s[40:41]
	s_nop 0
	v_cndmask_b32_e32 v111, v234, v111, vcc
	v_cndmask_b32_e64 v95, v234, v95, s[20:21]
.LBB0_500:
	v_max3_f32 v127, v0, v96, v80
	v_max3_f32 v127, v127, v97, v81
	v_max3_f32 v127, v127, v98, v82
	v_max3_f32 v127, v127, v99, v83
	v_max3_f32 v127, v127, v100, v84
	v_max3_f32 v127, v127, v101, v85
	v_max3_f32 v127, v127, v102, v86
	v_max3_f32 v127, v127, v103, v87
	v_max3_f32 v127, v127, v104, v88
	v_max3_f32 v127, v127, v105, v89
	v_max3_f32 v127, v127, v106, v90
	v_max3_f32 v127, v127, v107, v91
	v_max3_f32 v127, v127, v108, v92
	v_max3_f32 v127, v127, v109, v93
	v_max3_f32 v127, v127, v110, v94
	v_max3_f32 v127, v127, v111, v95
	ds_bpermute_b32 v136, v243, v127
	s_waitcnt lgkmcnt(0)
	v_max3_f32 v127, v127, v127, v136
	v_cmp_lt_f32_e32 vcc, s33, v127
	s_cbranch_vccz .LBB0_502
	v_exp_f32_e64 v136, -v127
	v_add_f32_e32 v239, v239, v127
	v_sub_f32_e32 v111, v111, v127
	v_sub_f32_e32 v110, v110, v127
	v_sub_f32_e32 v109, v109, v127
	v_sub_f32_e32 v108, v108, v127
	v_sub_f32_e32 v107, v107, v127
	v_sub_f32_e32 v106, v106, v127
	v_sub_f32_e32 v105, v105, v127
	v_sub_f32_e32 v104, v104, v127
	v_sub_f32_e32 v103, v103, v127
	v_sub_f32_e32 v102, v102, v127
	v_sub_f32_e32 v101, v101, v127
	v_sub_f32_e32 v100, v100, v127
	v_sub_f32_e32 v99, v99, v127
	v_sub_f32_e32 v98, v98, v127
	v_sub_f32_e32 v97, v97, v127
	v_sub_f32_e32 v96, v96, v127
	v_pk_mul_f32 v[46:47], v[46:47], v[136:137] op_sel_hi:[1,0]
	v_pk_mul_f32 v[44:45], v[44:45], v[136:137] op_sel_hi:[1,0]
	v_pk_mul_f32 v[42:43], v[42:43], v[136:137] op_sel_hi:[1,0]
	v_pk_mul_f32 v[40:41], v[40:41], v[136:137] op_sel_hi:[1,0]
	v_pk_mul_f32 v[38:39], v[38:39], v[136:137] op_sel_hi:[1,0]
	v_pk_mul_f32 v[36:37], v[36:37], v[136:137] op_sel_hi:[1,0]
	v_pk_mul_f32 v[34:35], v[34:35], v[136:137] op_sel_hi:[1,0]
	v_pk_mul_f32 v[32:33], v[32:33], v[136:137] op_sel_hi:[1,0]
	v_pk_mul_f32 v[30:31], v[30:31], v[136:137] op_sel_hi:[1,0]
	v_pk_mul_f32 v[28:29], v[28:29], v[136:137] op_sel_hi:[1,0]
	v_pk_mul_f32 v[26:27], v[26:27], v[136:137] op_sel_hi:[1,0]
	v_pk_mul_f32 v[24:25], v[24:25], v[136:137] op_sel_hi:[1,0]
	v_pk_mul_f32 v[22:23], v[22:23], v[136:137] op_sel_hi:[1,0]
	v_pk_mul_f32 v[20:21], v[20:21], v[136:137] op_sel_hi:[1,0]
	v_pk_mul_f32 v[18:19], v[18:19], v[136:137] op_sel_hi:[1,0]
	v_pk_mul_f32 v[16:17], v[16:17], v[136:137] op_sel_hi:[1,0]
	v_mul_f32_e32 v238, v238, v136
	v_sub_f32_e32 v95, v95, v127
	v_sub_f32_e32 v94, v94, v127
	v_sub_f32_e32 v93, v93, v127
	v_sub_f32_e32 v92, v92, v127
	v_sub_f32_e32 v91, v91, v127
	v_sub_f32_e32 v90, v90, v127
	v_sub_f32_e32 v89, v89, v127
	v_sub_f32_e32 v88, v88, v127
	v_sub_f32_e32 v87, v87, v127
	v_sub_f32_e32 v86, v86, v127
	v_sub_f32_e32 v85, v85, v127
	v_sub_f32_e32 v84, v84, v127
	v_sub_f32_e32 v83, v83, v127
	v_sub_f32_e32 v82, v82, v127
	v_sub_f32_e32 v81, v81, v127
	v_sub_f32_e32 v80, v80, v127
